# P1 row-norm phase: nt (streaming) policy on the once-read x row loads and per-batch factor loads
# speedup vs baseline: 1.0384x; 1.0036x over previous
.LBB0_237:
	s_lshl_b32 s2, s60, 3
	s_add_i32 s26, s8, s2
	s_mov_b64 s[6:7], s[0:1]
	s_mov_b64 s[4:5], s[0:1]
	s_mov_b64 s[10:11], s[0:1]
	s_mov_b64 s[12:13], s[0:1]
	s_mov_b64 s[18:19], s[0:1]
	s_mov_b64 s[14:15], s[0:1]
	s_cmpk_gt_i32 s26, 0x7fff
	s_cbranch_scc1 .LBB0_246
	s_load_dwordx2 s[16:17], s[6:7], 0x0
	s_ashr_i32 s27, s26, 31
	s_lshl_b32 s6, s22, 3
	s_lshl_b64 s[8:9], s[26:27], 12
	v_lshlrev_b32_e32 v64, 4, v0
	s_waitcnt lgkmcnt(0)
	s_add_u32 s8, s16, s8
	s_addc_u32 s9, s17, s9
	global_load_dwordx4 v[60:63], v64, s[8:9] nt
	global_load_dwordx4 v[56:59], v64, s[8:9] offset:1024 nt
	global_load_dwordx4 v[52:55], v64, s[8:9] offset:2048 nt
	global_load_dwordx4 v[32:35], v64, s[8:9] offset:3072 nt
	v_mbcnt_hi_u32_b32 v1, -1, v222
	v_and_b32_e32 v3, 64, v1
	v_add_u32_e32 v3, 64, v3
	v_xor_b32_e32 v4, 32, v1
	v_cmp_lt_i32_e32 vcc, v4, v3
	s_load_dwordx2 s[20:21], s[4:5], 0x20
	s_load_dwordx2 s[8:9], s[10:11], 0xa0
	s_load_dwordx2 s[24:25], s[12:13], 0x98
	s_load_dwordx2 s[28:29], s[18:19], 0xa0
	s_load_dwordx2 s[30:31], s[14:15], 0xa0
	v_cndmask_b32_e32 v4, v1, v4, vcc
	v_lshlrev_b32_e32 v74, 2, v4
	v_xor_b32_e32 v4, 16, v1
	v_cmp_lt_i32_e32 vcc, v4, v3
	s_lshl_b64 s[10:11], s[26:27], 2
	s_waitcnt lgkmcnt(0)
	s_add_u32 s3, s28, s10
	v_cndmask_b32_e32 v4, v1, v4, vcc
	v_lshlrev_b32_e32 v75, 2, v4
	v_xor_b32_e32 v4, 8, v1
	v_cmp_lt_i32_e32 vcc, v4, v3
	s_addc_u32 s7, s29, s11
	s_add_u32 s10, s3, 0x500000
	v_cndmask_b32_e32 v4, v1, v4, vcc
	v_lshlrev_b32_e32 v76, 2, v4
	v_xor_b32_e32 v4, 4, v1
	v_cmp_lt_i32_e32 vcc, v4, v3
	s_addc_u32 s11, s7, 0
	s_ashr_i32 s7, s6, 31
	v_cndmask_b32_e32 v4, v1, v4, vcc
	v_lshlrev_b32_e32 v77, 2, v4
	v_xor_b32_e32 v4, 2, v1
	v_cmp_lt_i32_e32 vcc, v4, v3
	s_lshl_b64 s[12:13], s[6:7], 2
	s_lshl_b64 s[14:15], s[26:27], 10
	v_cndmask_b32_e32 v4, v1, v4, vcc
	v_mov_b32_e32 v65, 0
	v_lshlrev_b32_e32 v78, 2, v4
	v_xor_b32_e32 v4, 1, v1
	s_add_u32 s14, s24, s14
	v_lshlrev_b32_e32 v2, 2, v0
	v_cmp_lt_i32_e32 vcc, v4, v3
	v_mov_b32_e32 v3, v65
	s_addc_u32 s15, s25, s15
	v_lshl_add_u64 v[70:71], s[14:15], 0, v[2:3]
	s_lshl_b64 s[14:15], s[6:7], 10
	s_lshl_b64 s[18:19], s[26:27], 11
	s_add_u32 s18, s30, s18
	v_lshl_add_u64 v[66:67], s[16:17], 0, v[64:65]
	v_cndmask_b32_e32 v1, v1, v4, vcc
	v_lshl_add_u64 v[68:69], s[20:21], 0, v[64:65]
	v_lshlrev_b32_e32 v64, 3, v0
	s_addc_u32 s19, s31, s19
	v_lshlrev_b32_e32 v79, 2, v1
	v_cmp_eq_u32_e64 s[4:5], 0, v0
	v_or_b32_e32 v4, 0x100, v2
	v_or_b32_e32 v6, 0x200, v2
	v_or_b32_e32 v8, 0x300, v2
	v_lshl_add_u64 v[0:1], s[18:19], 0, v[64:65]
	s_mov_b64 s[18:19], 0x3000000
	s_mov_b32 s17, -1
	v_lshl_add_u64 v[72:73], v[0:1], 0, s[18:19]
	s_lshl_b64 s[18:19], s[6:7], 11
	v_lshlrev_b32_e32 v64, 2, v2
	v_lshlrev_b32_e32 v80, 2, v4
	v_lshlrev_b32_e32 v81, 2, v6
	v_lshlrev_b32_e32 v82, 2, v8
	v_mov_b32_e32 v83, 0x358637bd
	s_mov_b32 s3, 0x800000
	s_mov_b32 s7, 0x42fe0000
	s_mov_b32 s16, 0x40c0c00
	s_branch .LBB0_240

.LBB0_240:
	s_add_i32 s20, s26, s6
	s_cmpk_gt_i32 s20, 0x7fff
	s_cselect_b64 s[24:25], -1, 0
	s_and_b64 vcc, exec, s[24:25]
	s_waitcnt vmcnt(3)
	v_mov_b32_e32 v12, v60
	v_mov_b32_e32 v13, v61
	v_mov_b32_e32 v14, v62
	v_mov_b32_e32 v15, v63
	s_waitcnt vmcnt(2)
	v_mov_b32_e32 v16, v56
	v_mov_b32_e32 v17, v57
	v_mov_b32_e32 v18, v58
	v_mov_b32_e32 v19, v59
	s_waitcnt vmcnt(1)
	v_mov_b32_e32 v20, v52
	v_mov_b32_e32 v21, v53
	v_mov_b32_e32 v22, v54
	v_mov_b32_e32 v23, v55
	s_waitcnt vmcnt(0)
	v_mov_b32_e32 v24, v32
	v_mov_b32_e32 v25, v33
	v_mov_b32_e32 v26, v34
	v_mov_b32_e32 v27, v35
	s_cbranch_vccnz .LBB0_242
	s_ashr_i32 s21, s20, 31
	s_lshl_b64 s[28:29], s[20:21], 12
	v_lshl_add_u64 v[84:85], v[66:67], 0, s[28:29]
	global_load_dwordx4 v[12:15], v[84:85], off nt
	global_load_dwordx4 v[16:19], v[84:85], off offset:1024 nt
	global_load_dwordx4 v[20:23], v[84:85], off offset:2048 nt
	global_load_dwordx4 v[24:27], v[84:85], off offset:3072 nt
.LBB0_242:
	s_ashr_i32 s21, s26, 13
	s_cmp_eq_u32 s21, s17
	s_cbranch_scc1 .LBB0_244
	s_mul_i32 s26, s21, 0x1800
	s_ashr_i32 s27, s26, 31
	s_lshl_b64 s[26:27], s[26:27], 2
	s_add_u32 s26, s8, s26
	s_addc_u32 s27, s9, s27
	s_add_u32 s28, s26, 0x1000
	s_addc_u32 s29, s27, 0
	global_load_dwordx4 v[36:39], v64, s[28:29] nt
	global_load_dwordx4 v[40:43], v80, s[28:29] nt
	global_load_dwordx4 v[44:47], v81, s[28:29] nt
	global_load_dwordx4 v[48:51], v82, s[28:29] nt
	global_load_dwordx4 v[84:87], v[68:69], off nt
	global_load_dwordx4 v[88:91], v[68:69], off offset:1024 nt
	global_load_dwordx4 v[92:95], v[68:69], off offset:2048 nt
	global_load_dwordx4 v[96:99], v[68:69], off offset:3072 nt
	global_load_dwordx4 v[8:11], v64, s[26:27] nt
	global_load_dwordx4 v[4:7], v64, s[26:27] offset:1024 nt
	global_load_dwordx4 v[0:3], v64, s[26:27] offset:2048 nt
	global_load_dwordx4 v[28:31], v64, s[26:27] offset:3072 nt
	s_mov_b32 s17, s21
	s_waitcnt vmcnt(11)
	v_pk_add_f32 v[38:39], v[38:39], 1.0 op_sel_hi:[1,0]
	v_pk_add_f32 v[36:37], v[36:37], 1.0 op_sel_hi:[1,0]
	s_waitcnt vmcnt(10)
	v_pk_add_f32 v[42:43], v[42:43], 1.0 op_sel_hi:[1,0]
	v_pk_add_f32 v[40:41], v[40:41], 1.0 op_sel_hi:[1,0]
	s_waitcnt vmcnt(9)
	v_pk_add_f32 v[46:47], v[46:47], 1.0 op_sel_hi:[1,0]
	v_pk_add_f32 v[44:45], v[44:45], 1.0 op_sel_hi:[1,0]
	s_waitcnt vmcnt(8)
	v_pk_add_f32 v[50:51], v[50:51], 1.0 op_sel_hi:[1,0]
	v_pk_add_f32 v[48:49], v[48:49], 1.0 op_sel_hi:[1,0]
	s_waitcnt vmcnt(7)
	v_pk_mul_f32 v[38:39], v[86:87], v[38:39]
	v_pk_mul_f32 v[36:37], v[84:85], v[36:37]
	s_waitcnt vmcnt(6)
	v_pk_mul_f32 v[42:43], v[90:91], v[42:43]
	v_pk_mul_f32 v[40:41], v[88:89], v[40:41]
	s_waitcnt vmcnt(5)
	v_pk_mul_f32 v[46:47], v[94:95], v[46:47]
	v_pk_mul_f32 v[44:45], v[92:93], v[44:45]
	s_waitcnt vmcnt(4)
	v_pk_mul_f32 v[50:51], v[98:99], v[50:51]
	v_pk_mul_f32 v[48:49], v[96:97], v[48:49]
